# attn_prompt: static s_setprio 1 for waves 4..7 (second wave of each SIMD) during the phase, reset at the start of attn_sample
# speedup vs baseline: 1.0130x; 1.0130x over previous
; __device__ __forceinline__ void attn_prompt(const Params& p, int j, LAS unsigned char* lds, const int wave, const int lane) {
;     ...
;     int bt = blockIdx.x;
;     if (bt < 3072) ATT_LOAD(bt);
;     for (; bt < 3072; bt += gridDim.x) {
.LBB0_292:
	v_readlane_b32 s100, v251, 0
	s_nop 1
	s_cmp_lt_u32 s100, 4
	s_cbranch_scc1 .Lap_prio_skip
	s_setprio 1

; #define LAS __attribute__((address_space(3)))
; __device__ __forceinline__ void attn_sample(const Params& p, int j, LAS unsigned char* lds, int gw, int NGW, int wave, int lane) {
;     unsigned char* ws = p.ws;
;     const bf16_t* P = (const bf16_t*)(ws + WS_P);
;     LAS float* scs = (LAS float*)(lds + 40960 + wave * 2560);
;     const int rs = lane >> 4, ch = lane & 15;
;     for (int task = gw; task < NS * 8; task += NGW) {
;         const int t = task & 7, h = (task >> 3) & 7, b = task >> 6, s = b * 8 + t, n = NP + s;
.LBB0_322:
	s_setprio 0
	v_readlane_b32 s2, v251, 0
	v_readlane_b32 s0, v251, 8
	s_add_i32 s0, s2, s0
	s_mov_b32 s3, -1
	s_cmpk_gt_i32 s0, 0x7ff
	s_cbranch_scc1 .LBB0_631
	s_waitcnt vmcnt(3)
	v_mbcnt_lo_u32_b32 v0, s3, 0
	v_mbcnt_hi_u32_b32 v1, s3, v0
	s_mul_i32 s3, s2, 0xa00
	v_lshrrev_b32_e32 v65, 4, v1
	s_movk_i32 s12, 0x183
	v_and_b32_e32 v0, 15, v1
	v_cmp_gt_i32_e64 s[38:39], s12, v1
	s_and_b32 s47, s2, 7
	v_lshl_or_b32 v2, v65, 2, s3
	s_add_i32 s2, 0, 0xa000
	v_readlane_b32 s12, v255, 8
	v_lshlrev_b32_e32 v64, 2, v0
	v_cmp_eq_u32_e64 s[36:37], 0, v0
	v_lshlrev_b32_e32 v0, 2, v1
	v_add_u32_e32 v83, s2, v2
	v_add_u32_e32 v85, s12, v2
	v_readlane_b32 s12, v255, 9
	s_add_i32 s2, s2, s3
	s_lshl_b32 s5, s56, 5
	s_add_i32 s7, s3, 0
	v_cmp_gt_u32_e64 s[40:41], 16, v1
	s_or_b32 s17, s47, 0x4000
	s_or_b32 s34, s47, 0x80
	s_or_b32 s46, s47, 0x200
	s_bitset1_b32 s47, 11
	v_add_u32_e32 v87, s12, v2
	v_add_u32_e32 v89, s2, v0
	v_subrev_u32_e32 v91, 64, v1
	v_lshlrev_b32_e32 v66, 1, v0
	s_branch .LBB0_325
